# P1: the 159 workgroups that only have 8 tiles start ~15us late (half a tile period) so their epilogue store bursts interleave with the 9-tile workgroups' K-loops; + ssq/gate-broadcast LDS round trips
# baseline (speedup 1.0000x reference)
; __device__ __forceinline__ int opaque_s(int x) { asm volatile("" : "+s"(x)); return x; }
; __global__ void __launch_bounds__(512) hybrid_step_fwd(Params P) {
;     ...
;     const XcdBarrier xb = xcd_barrier_post(barw, xst);
;     ...
; #pragma nounroll
;     for (int rep = 0, nrep = opaque_s(REP_P1); rep < nrep; ++rep) {
;         pg8::Gemm g{(const bf16*)(ws + WS_XN), (const bf16*)(ws + WS_WIN), MPAD, NZ, DM, DM, DM}; pg8::StaticOrder S; S.init(MPAD, NZ, G, (int)blockIdx.x);
;         pg8::EpiZ E{(bf16*)(ws + WS_Z), (bf16*)(ws + WS_VT), (const float*)(ws + WS_ROPE), P.out};
;         pg8::gemm_phase<pg8::EpiZ, pg8::StaticOrder, true, true>(lds, g, S, E);
.LBB0_109:
	s_getreg_b32 s0, hwreg(HW_REG_XCC_ID, 0, 4)
	s_and_b32 s0, s0, 15
	v_writelane_b32 v252, s0, 10
	v_readlane_b32 s1, v252, 0
	s_nop 3
	s_cmp_lt_u32 s1, 97
	s_cbranch_scc1 .Lstag1_done
	s_sleep 127
	s_sleep 127
	s_sleep 127
	s_sleep 127

; #define LAS __attribute__((address_space(3)))
; __device__ __forceinline__ float sum_x16(float v) { return v + __shfl_xor(v, 16); }
; __device__ __forceinline__ void mlstm_unit(const Params& P, LAS unsigned char* lds, int unit) {
;     ...
;             {
;                 const int tt = tid >> 3, part = tid & 7;
; #pragma unroll
;                 for (int c = 0; c < 4; ++c) { const u32x4v qv = *(const LAS u32x4v*)(lds + ML_QS + tt * QROW + (32 * part + 8 * c) * 2);
;                     const f32x4v n0 = *(const LAS f32x4v*)(nS + 32 * part + 8 * c), n1 = *(const LAS f32x4v*)(nS + 32 * part + 8 * c + 4);
;                     qd += bflo(qv.x) * n0[0] + bfhi(qv.x) * n0[1] + bflo(qv.y) * n0[2] + bfhi(qv.y) * n0[3] + bflo(qv.z) * n1[0] + bfhi(qv.z) * n1[1] + bflo(qv.w) * n1[2] + bfhi(qv.w) * n1[3]; }
;             }
;             __builtin_amdgcn_sched_barrier(0);
; #pragma unroll
;             for (int nn = 0; nn < 2; ++nn) {
;                 const int nt = ntb + nn;
;                 pg8::f32x4 acc = (pg8::f32x4){0.f, 0.f, 0.f, 0.f};
;                 float rsum = 0.f;
;                 if (nt <= mt) {
;                     bf16x8m bfr[8];
; #pragma unroll
;                     for (int ks = 0; ks < 8; ++ks) bfr[ks] = *(const LAS bf16x8m*)(lds + ML_KS + (16 * nt + fr) * QROW + (32 * ks + 8 * fq) * 2);
;                     __builtin_amdgcn_sched_barrier(0);
; #pragma unroll
;                     for (int ks = 0; ks < 8; ++ks) acc = MFMA16(bfr[ks], af[ks], acc);
; #pragma unroll
;                     for (int i = 0; i < 4; ++i) { const int s = 16 * nt + 4 * fq + i; const float p = (s <= t) ? acc[i] * exp_(as_[nn][i] - Mt) : 0.f; acc[i] = p; rsum += p; }
;                 }
;                 rsum = sum_x32(sum_x16(rsum));
;                 if (fq == 0) rsS[t * 4 + nt] = rsum;
;                 u32x2v pw; pw.x = pk2(acc[0], acc[1]); pw.y = pk2(acc[2], acc[3]);
;                 *(LAS u32x2v*)(lds + ML_PS + t * PROW + (16 * nt + 4 * fq) * 2) = pw;
;             }
;             qd = sum_grp8(qd);
;             if ((tid & 7) == 0) qnS[tid >> 3] = qd;
;         }
;         ML_BAR();
;         const int dt = w & 1;
;         bf16x8m pa[2], vb[2], cb[8];
; #pragma unroll
;         for (int ks = 0; ks < 2; ++ks) {
;             pa[ks] = *(const LAS bf16x8m*)(lds + ML_PS + (16 * mt + fr) * PROW + (32 * ks + 8 * fq) * 2);
.LBB0_499:
	s_or_b64 exec, exec, s[18:19]
	v_lshlrev_b32_e32 v173, 16, v124
	v_and_b32_e32 v124, 0xffff0000, v124
	v_mul_f32_e32 v124, v133, v124
	v_fmac_f32_e32 v124, v132, v173
	v_lshlrev_b32_e32 v173, 16, v125
	v_fmac_f32_e32 v124, v134, v173
	v_and_b32_e32 v173, 0xffff0000, v125
	v_fmac_f32_e32 v124, v135, v173
	v_lshlrev_b32_e32 v173, 16, v126
	v_fmac_f32_e32 v124, v128, v173
	v_and_b32_e32 v173, 0xffff0000, v126
	v_fmac_f32_e32 v124, v129, v173
	v_lshlrev_b32_e32 v173, 16, v127
	v_fmac_f32_e32 v124, v130, v173
	v_and_b32_e32 v173, 0xffff0000, v127
	v_fmac_f32_e32 v124, v131, v173
	v_lshlrev_b32_e32 v173, 16, v112
	v_and_b32_e32 v112, 0xffff0000, v112
	v_mul_f32_e32 v112, v121, v112
	v_fmac_f32_e32 v112, v120, v173
	v_lshlrev_b32_e32 v173, 16, v113
	v_fmac_f32_e32 v112, v122, v173
	v_and_b32_e32 v173, 0xffff0000, v113
	v_fmac_f32_e32 v112, v123, v173
	v_lshlrev_b32_e32 v173, 16, v114
	v_fmac_f32_e32 v112, v116, v173
	v_and_b32_e32 v173, 0xffff0000, v114
	v_fmac_f32_e32 v112, v117, v173
	v_lshlrev_b32_e32 v173, 16, v115
	v_fmac_f32_e32 v112, v118, v173
	v_and_b32_e32 v173, 0xffff0000, v115
	v_fmac_f32_e32 v112, v119, v173
	v_lshlrev_b32_e32 v173, 16, v100
	v_and_b32_e32 v100, 0xffff0000, v100
	v_mul_f32_e32 v100, v109, v100
	v_fmac_f32_e32 v100, v108, v173
	v_lshlrev_b32_e32 v173, 16, v101
	v_fmac_f32_e32 v100, v110, v173
	v_and_b32_e32 v173, 0xffff0000, v101
	v_fmac_f32_e32 v100, v111, v173
	v_lshlrev_b32_e32 v173, 16, v102
	v_fmac_f32_e32 v100, v104, v173
	v_and_b32_e32 v173, 0xffff0000, v102
	v_fmac_f32_e32 v100, v105, v173
	v_lshlrev_b32_e32 v173, 16, v103
	v_fmac_f32_e32 v100, v106, v173
	v_and_b32_e32 v173, 0xffff0000, v103
	v_fmac_f32_e32 v100, v107, v173
	v_lshlrev_b32_e32 v173, 16, v88
	v_and_b32_e32 v88, 0xffff0000, v88
	v_mul_f32_e32 v97, v97, v88
	v_fmac_f32_e32 v97, v96, v173
	v_lshlrev_b32_e32 v173, 16, v89
	v_fmac_f32_e32 v97, v98, v173
	v_and_b32_e32 v173, 0xffff0000, v89
	v_fmac_f32_e32 v97, v99, v173
	v_lshlrev_b32_e32 v173, 16, v90
	v_fmac_f32_e32 v97, v92, v173
	v_and_b32_e32 v173, 0xffff0000, v90
	v_fmac_f32_e32 v97, v93, v173
	v_lshlrev_b32_e32 v173, 16, v91
	v_fmac_f32_e32 v97, v94, v173
	v_and_b32_e32 v173, 0xffff0000, v91
	v_fmac_f32_e32 v97, v95, v173
	v_add_f32_e32 v173, 0, v124
	v_add_f32_e32 v173, v173, v112
	v_add_f32_e32 v173, v173, v100
	v_add_f32_e32 v173, v173, v97
	v_cvt_pk_bf16_f32 v88, v142, v143
	v_cvt_pk_bf16_f32 v89, v144, v221
	v_add_f32_dpp v173, v173, v173 quad_perm:[1,0,3,2] row_mask:0xf bank_mask:0xf bound_ctrl:1
	ds_write_b64 v200, v[88:89]
	s_nop 0
	v_add_f32_dpp v173, v173, v173 quad_perm:[2,3,0,1] row_mask:0xf bank_mask:0xf bound_ctrl:1
	s_nop 1
	v_mov_b32_dpp v88, v173 row_half_mirror row_mask:0xf bank_mask:0xf bound_ctrl:1
	s_and_saveexec_b64 s[18:19], s[4:5]
	v_add_f32_e32 v173, v173, v88
	ds_write_b32 v186, v173
	s_or_b64 exec, exec, s[18:19]
	s_waitcnt lgkmcnt(0)
	s_barrier
	v_add_u32_e32 v104, v207, v206
	ds_read_b64_tr_b16 v[92:93], v193
	ds_read_b128 v[96:99], v104 offset:64
	ds_read_b64_tr_b16 v[94:95], v190
	ds_read_b64_tr_b16 v[100:101], v191
	ds_read_b64_tr_b16 v[102:103], v192
	ds_read_b128 v[106:109], v189
	ds_read_b128 v[110:113], v189 offset:64
	ds_read_b128 v[114:117], v189 offset:128
	ds_read_b128 v[118:121], v189 offset:192
	ds_read_b32 v90, v182
	ds_read_b32 v173, v181
	ds_read_b32 v91, v180
	ds_read_b128 v[122:125], v177
	ds_read_b128 v[126:129], v189 offset:256
	ds_read_b128 v[130:133], v189 offset:320
	s_waitcnt lgkmcnt(14)
	ds_read_b128 v[134:137], v189 offset:384
	ds_read_b128 v[168:171], v189 offset:448
	s_waitcnt lgkmcnt(4)
	v_mov_b32_e32 v88, v123
	v_mov_b32_e32 v89, v124
	v_mov_b32_e32 v123, v125
	v_mov_b32_e32 v105, s26
	v_pk_add_f32 v[88:89], v[88:89], v[122:123]
	s_nop 0
	v_add_f32_e32 v89, v88, v89
	ds_read_b32 v88, v105
	ds_read_b128 v[122:125], v188 offset:33792
	ds_read_b128 v[222:225], v104
	ds_read_b128 v[226:229], v184
	ds_read_b128 v[230:233], v187 offset:33792
	ds_read_b128 v[234:237], v187 offset:34320
	ds_read_b128 v[238:241], v187 offset:34848
	s_waitcnt lgkmcnt(5)
	v_lshlrev_b32_e32 v138, 16, v122
	v_and_b32_e32 v139, 0xffff0000, v122
	s_waitcnt lgkmcnt(3)
	v_pk_fma_f32 v[138:139], v[226:227], v[138:139], 0 op_sel_hi:[0,1,0]
	s_waitcnt lgkmcnt(2)
	v_lshlrev_b32_e32 v142, 16, v230
	v_and_b32_e32 v143, 0xffff0000, v230
	v_pk_fma_f32 v[138:139], v[226:227], v[142:143], v[138:139] op_sel:[1,0,0]
	s_waitcnt lgkmcnt(1)
	v_lshlrev_b32_e32 v142, 16, v234
	v_and_b32_e32 v143, 0xffff0000, v234
	v_pk_fma_f32 v[138:139], v[228:229], v[142:143], v[138:139] op_sel_hi:[0,1,1]
	s_waitcnt lgkmcnt(0)
; __device__ __forceinline__ unsigned pk2(float lo, float hi) { const f32x2v v = {lo, hi}; return __builtin_bit_cast(unsigned, __builtin_convertvector(v, bf16x2_hw)); }
; __device__ __forceinline__ float sum_x16(float v) { return v + __shfl_xor(v, 16); }
; __device__ __forceinline__ float sum_x32(float v) { return v + __shfl_xor(v, 32); }
; #define MFMA16(a, b, c) __builtin_amdgcn_mfma_f32_16x16x32_bf16((a), (b), (c), 0, 0, 0)
; __device__ __forceinline__ void mlstm_unit(const Params& P, LAS unsigned char* lds, int unit) {
;     ...
;             pg8::f32x4 acc1 = (pg8::f32x4){0.f, 0.f, 0.f, 0.f}, acc2 = (pg8::f32x4){0.f, 0.f, 0.f, 0.f};
; #pragma unroll
;             for (int ks = 0; ks < 2; ++ks) acc1 = MFMA16(vb[ks], pa[ks], acc1);
; #pragma unroll
;             for (int ks = 0; ks < 8; ++ks) acc2 = MFMA16(cb[ks], af[ks], acc2);
;             bf16x8m va[2][2], kb[2][2];
; #pragma unroll
;             for (int ks = 0; ks < 2; ++ks) {
; #pragma unroll
;                 for (int dvt = 0; dvt < 2; ++dvt) { const v4i16_t lo = ldtr(lds + ML_VW + 32 * ks * VROW + trv + 32 * dvt), hi = ldtr(lds + ML_VW + (32 * ks + 4) * VROW + trv + 32 * dvt); va[dvt][ks] = __builtin_shufflevector(lo, hi, 0, 1, 2, 3, 4, 5, 6, 7); }
; #pragma unroll
;                 for (int nk = 0; nk < 2; ++nk) { const v4i16_t lo = ldtr(lds + ML_KS + 32 * ks * QROW + trk + 32 * (2 * w + nk)), hi = ldtr(lds + ML_KS + (32 * ks + 4) * QROW + trk + 32 * (2 * w + nk)); kb[nk][ks] = __builtin_shufflevector(lo, hi, 0, 1, 2, 3, 4, 5, 6, 7); }
;             }
; #pragma unroll
;             for (int dvt = 0; dvt < 2; ++dvt)
; #pragma unroll
;                 for (int nk = 0; nk < 2; ++nk) {
;                     pg8::f32x4 c = Cacc[dvt][nk] * decay;
; #pragma unroll
;                     for (int ks = 0; ks < 2; ++ks) c = MFMA16(kb[nk][ks], va[dvt][ks], c);
;                     Cacc[dvt][nk] = c;
;                 }
;             const float inv = __builtin_amdgcn_rcpf(dn);
;             float hv[4]; float sq = 0.f;
; #pragma unroll
;             for (int i = 0; i < 4; ++i) { hv[i] = (acc1[i] + wi * acc2[i]) * inv; sq += hv[i] * hv[i]; }
;             u32x2v hw; hw.x = pk2(hv[0], hv[1]); hw.y = pk2(hv[2], hv[3]);
;             *(u32x2v*)(HB + (size_t)(t0 + t) * DM + 16 * dt + 4 * fq) = hw;
;             sq = sum_x32(sum_x16(sq));
;             if (fq == 0) SSQ[(size_t)(t0 + t) * 64 + dt] = sq;
	v_lshlrev_b32_e32 v142, 16, v238
	v_and_b32_e32 v143, 0xffff0000, v238
	v_mov_b32_e32 v144, v229
	v_lshlrev_b32_e32 v122, 16, v123
	v_and_b32_e32 v123, 0xffff0000, v123
	v_pk_fma_f32 v[242:243], v[144:145], v[142:143], v[138:139] op_sel_hi:[0,1,1]
	v_pk_fma_f32 v[122:123], v[226:227], v[122:123], 0 op_sel_hi:[0,1,0]
	v_lshlrev_b32_e32 v138, 16, v231
	v_and_b32_e32 v139, 0xffff0000, v231
	v_pk_fma_f32 v[122:123], v[226:227], v[138:139], v[122:123] op_sel:[1,0,0]
	v_lshlrev_b32_e32 v138, 16, v235
	v_and_b32_e32 v139, 0xffff0000, v235
	v_pk_fma_f32 v[122:123], v[228:229], v[138:139], v[122:123] op_sel_hi:[0,1,1]
	v_lshlrev_b32_e32 v138, 16, v239
	v_and_b32_e32 v139, 0xffff0000, v239
	v_pk_fma_f32 v[244:245], v[144:145], v[138:139], v[122:123] op_sel_hi:[0,1,1]
	v_lshlrev_b32_e32 v122, 16, v124
	v_and_b32_e32 v123, 0xffff0000, v124
	v_pk_fma_f32 v[122:123], v[226:227], v[122:123], 0 op_sel_hi:[0,1,0]
	v_lshlrev_b32_e32 v138, 16, v232
	v_and_b32_e32 v139, 0xffff0000, v232
	v_pk_fma_f32 v[122:123], v[226:227], v[138:139], v[122:123] op_sel:[1,0,0]
	v_lshlrev_b32_e32 v138, 16, v236
	v_and_b32_e32 v139, 0xffff0000, v236
	v_pk_fma_f32 v[122:123], v[228:229], v[138:139], v[122:123] op_sel_hi:[0,1,1]
	v_lshlrev_b32_e32 v138, 16, v240
	v_and_b32_e32 v139, 0xffff0000, v240
	v_lshlrev_b32_e32 v124, 16, v125
	v_and_b32_e32 v125, 0xffff0000, v125
	v_pk_fma_f32 v[122:123], v[144:145], v[138:139], v[122:123] op_sel_hi:[0,1,1]
	v_pk_fma_f32 v[124:125], v[226:227], v[124:125], 0 op_sel_hi:[0,1,0]
	v_lshlrev_b32_e32 v138, 16, v233
	v_and_b32_e32 v139, 0xffff0000, v233
	v_pk_fma_f32 v[124:125], v[226:227], v[138:139], v[124:125] op_sel:[1,0,0]
	v_lshlrev_b32_e32 v138, 16, v237
	v_and_b32_e32 v139, 0xffff0000, v237
	v_pk_fma_f32 v[124:125], v[228:229], v[138:139], v[124:125] op_sel_hi:[0,1,1]
	v_lshlrev_b32_e32 v138, 16, v241
	v_and_b32_e32 v139, 0xffff0000, v241
	v_fmac_f32_e32 v89, v90, v173
	v_pk_fma_f32 v[124:125], v[144:145], v[138:139], v[124:125] op_sel_hi:[0,1,1]
	ds_write_b128 v185, v[242:245]
	ds_write_b128 v185, v[122:125] offset:16
	v_mfma_f32_16x16x32_bf16 v[84:87], v[106:109], v[84:87], 0
	v_add_u32_e32 v173, 0, v204
	v_add_u32_e32 v106, 0x19800, v173
	v_add_u32_e32 v108, 0x19940, v173
	v_mfma_f32_16x16x32_bf16 v[76:79], v[110:113], v[76:79], v[84:87]
	v_add_u32_e32 v107, 0x1a200, v173
	v_add_u32_e32 v109, 0x1a340, v173
	v_max_f32_e32 v173, v91, v91
	v_mfma_f32_16x16x32_bf16 v[76:79], v[114:117], v[80:83], v[76:79]
	v_max_f32_e64 v173, |v89|, v173
	v_pk_mul_f32 v[14:15], v[14:15], v[88:89] op_sel_hi:[1,0]
	v_pk_mul_f32 v[12:13], v[12:13], v[88:89] op_sel_hi:[1,0]
	v_mfma_f32_16x16x32_bf16 v[72:75], v[118:121], v[72:75], v[76:79]
	s_nop 3
	ds_read_b64_tr_b16 v[78:79], v108
	ds_read_b64_tr_b16 v[82:83], v108 offset:32
	ds_read_b64_tr_b16 v[76:77], v106
	ds_read_b64_tr_b16 v[80:81], v106 offset:32
	v_pk_mul_f32 v[10:11], v[10:11], v[88:89] op_sel_hi:[1,0]
	v_pk_mul_f32 v[8:9], v[8:9], v[88:89] op_sel_hi:[1,0]
	v_mfma_f32_16x16x32_bf16 v[68:71], v[126:129], v[68:71], v[72:75]
	s_nop 2
	ds_read_b64_tr_b16 v[74:75], v176 offset:35904
	ds_read_b64_tr_b16 v[72:73], v176 offset:33792
	ds_read_b64_tr_b16 v[86:87], v176 offset:35936
	ds_read_b64_tr_b16 v[84:85], v176 offset:33824
	v_pk_mul_f32 v[6:7], v[6:7], v[88:89] op_sel_hi:[1,0]
	v_pk_mul_f32 v[4:5], v[4:5], v[88:89] op_sel_hi:[1,0]
	v_mfma_f32_16x16x32_bf16 v[64:67], v[130:133], v[64:67], v[68:71]
	v_mul_f32_e64 v2, v2, v88
	v_mul_f32_e64 v3, v3, v88
	v_pk_mul_f32 v[0:1], v[0:1], v[88:89] op_sel_hi:[1,0]
	v_mfma_f32_16x16x32_bf16 v[92:95], v[92:95], v[222:225], 0
	v_mfma_f32_16x16x32_bf16 v[60:63], v[134:137], v[60:63], v[64:67]
	v_mfma_f32_16x16x32_bf16 v[92:95], v[100:103], v[96:99], v[92:95]
	ds_read_b64_tr_b16 v[70:71], v109
	ds_read_b64_tr_b16 v[98:99], v109 offset:32
	ds_read_b64_tr_b16 v[68:69], v107
	ds_read_b64_tr_b16 v[96:97], v107 offset:32
	ds_read_b64_tr_b16 v[64:65], v176 offset:50688
	ds_read_b64_tr_b16 v[66:67], v176 offset:52800
	ds_read_b64_tr_b16 v[102:103], v176 offset:52832
	ds_read_b64_tr_b16 v[100:101], v176 offset:50720
	v_mfma_f32_16x16x32_bf16 v[56:59], v[168:171], v[56:59], v[60:63]
	s_nop 2
	v_rcp_f32_e32 v60, v173
	s_waitcnt lgkmcnt(10)
	v_mfma_f32_16x16x32_bf16 v[12:15], v[72:75], v[76:79], v[12:15]
	s_nop 1
	v_fma_f32 v56, v90, v56, v92
	v_fma_f32 v57, v90, v57, v93
	v_pk_fma_f32 v[58:59], v[90:91], v[58:59], v[94:95] op_sel_hi:[0,1,1]
	v_pk_mul_f32 v[56:57], v[60:61], v[56:57] op_sel_hi:[0,1]
	v_pk_mul_f32 v[62:63], v[56:57], v[56:57]
	v_pk_mul_f32 v[58:59], v[60:61], v[58:59] op_sel_hi:[0,1]
	v_pk_mul_f32 v[60:61], v[58:59], v[58:59]
	v_add_f32_e32 v173, v62, v63
	v_add_f32_e32 v173, v60, v173
	v_add_f32_e32 v173, v61, v173
	v_mov_b32_e32 v60, v173
	v_mov_b32_e32 v61, v173
	s_waitcnt lgkmcnt(8)
	v_mfma_f32_16x16x32_bf16 v[8:11], v[84:87], v[76:79], v[8:11]
	v_permlane16_swap_b32_e32 v61, v60
	v_cvt_pk_bf16_f32 v56, v56, v57
	v_cvt_pk_bf16_f32 v57, v58, v59
	v_lshl_add_u64 v[58:59], s[14:15], 0, v[154:155]
	v_mfma_f32_16x16x32_bf16 v[4:7], v[72:75], v[80:83], v[4:7]
	s_waitcnt lgkmcnt(0)
	v_add_f32_e32 v173, v61, v60
	global_store_dwordx2 v[58:59], v[56:57], off
	v_mov_b32_e32 v60, v173
	v_mov_b32_e32 v61, v173
	v_mfma_f32_16x16x32_bf16 v[0:3], v[84:87], v[80:83], v[0:3]
	v_mfma_f32_16x16x32_bf16 v[12:15], v[64:67], v[68:71], v[12:15]
	v_permlane32_swap_b32_e32 v61, v60
	v_mfma_f32_16x16x32_bf16 v[8:11], v[100:103], v[68:71], v[8:11]
	v_mfma_f32_16x16x32_bf16 v[4:7], v[64:67], v[96:99], v[4:7]
	v_mfma_f32_16x16x32_bf16 v[0:3], v[100:103], v[96:99], v[0:3]
	s_and_saveexec_b64 s[18:19], s[40:41]
	s_cbranch_execz .LBB0_503
	v_lshl_add_u64 v[58:59], s[22:23], 0, v[152:153]
	v_add_f32_e32 v173, v61, v60
	global_store_dword v[58:59], v173, off

.LBB0_507:
	s_or_b64 exec, exec, s[18:19]
	s_and_saveexec_b64 s[18:19], s[42:43]
	s_cbranch_execz .LBB0_486
	v_max_f32_e32 v25, v22, v22
	v_max_f32_e32 v25, v24, v25
	v_add_f32_e32 v26, v20, v25
	s_nop 0
	v_readlane_b32 s99, v25, 63
	v_mul_f32_e32 v26, 0xbfb8aa3b, v26
	v_exp_f32_e32 v26, v26
	ds_write_b32 v209, v21
	ds_write_b32 v210, v25
	v_sub_f32_e32 v25, v173, v25
	v_mul_f32_e32 v25, 0x3fb8aa3b, v25
	ds_write_b32 v211, v26
	v_subrev_f32_e32 v26, s99, v21
	v_mul_f32_e32 v26, 0x3fb8aa3b, v26
	v_exp_f32_e32 v26, v26
	v_exp_f32_e32 v25, v25
	ds_write_b32 v212, v26
	ds_write_b32 v214, v25
	s_and_b64 exec, exec, s[60:61]
	s_cbranch_execz .LBB0_486
	v_subrev_f32_e32 v173, s99, v173
	v_mul_f32_e32 v173, 0x3fb8aa3b, v173
	v_exp_f32_e32 v173, v173
	v_mov_b32_e32 v24, s26
	ds_write_b32 v24, v173
	s_branch .LBB0_486
